# P4 queue loop: waves no longer drain their previous unit's stores before the ticket barrier (lgkmcnt only; wave 0 keeps its wait for the ticket atomic)
# speedup vs baseline: 1.0044x; 1.0010x over previous
; #define LAS __attribute__((address_space(3)))
; template <int NC, bool S16>
; __device__ __forceinline__ void p4_unit(LAS unsigned char* lds, const unsigned char* slot, const unsigned char* intra, const bf16* zg, const float* nw, bf16* out, const unsigned* done, bool valid) {
;     ...
;     if (valid) {
;     if (intra) {
; #pragma unroll
;         for (int k = 0; k < NBW; ++k) ivv[k] = ((const unsigned long long*)intra)[(w + 4 * k) * 64 + lane]; }
; __global__ void __launch_bounds__(512, 2) mega(MegaArgs a) {
;     ...
;                 for (;;) {
;                     if (tid == 0) ((LAS unsigned*)(lds + LDS_BAR))[3] = __hip_atomic_fetch_add(qhead, 2u, __ATOMIC_RELAXED, __HIP_MEMORY_SCOPE_AGENT);
;                     __syncthreads();
;                     const int j0 = (int)((LAS unsigned*)(lds + LDS_BAR))[3];
;                     __syncthreads();
;                     if (j0 >= NCH * (NPG + NPL)) break;
;                     const int j = j0 + hf; const bool valid = j < NCH * (NPG + NPL);
;                     const int rk = j / (NPG + NPL), idx = j % (NPG + NPL), n = (rk & 1) ? (NCH / 2 - 1 - (rk >> 1)) : (NCH / 2 + (rk >> 1));
;                     if ((j0 % (NPG + NPL)) < NPG) { const int u = idx * NCH + n, hd = idx % 8, sq = idx / 8;
;                         p4_unit<128, true>(lds_h, ws + WS_PG + 4 * PGMAT + (size_t)u * 16384, nullptr, (const bf16*)(ws + WS_Z) + ((size_t)sq * SEQ + n * CHUNK) * 1024 + hd * 128, a.in[8], ORAWA + (r0 + (size_t)sq * SEQ + n * CHUNK) * 1024 + hd * 128, gflag + (size_t)u * 8, valid); }
;                     else { const int pi = idx - NPG, u = pi * NCH + n, hd = pi % 4, sq = pi / 4;
;                         p4_unit<256, false>(lds_h, ws + WS_PG + 3 * PGMAT + (size_t)u * 32768, ws + WS_LBLOBB + (size_t)u * gla::BLOBB + gla::B_INTRA, nullptr, a.in[14], ORAWB + (r0 + (size_t)sq * SEQ + n * CHUNK) * 1024 + hd * 256, lflag + (size_t)u * 8, valid); }
.LBB0_675:
	s_or_b64 exec, exec, s[2:3]
	v_readlane_b32 s2, v254, 9
	s_waitcnt lgkmcnt(0)
	s_barrier
	v_mov_b32_e32 v2, s2
	ds_read_b32 v2, v2
	s_movk_i32 s2, 0x5ff
	s_waitcnt lgkmcnt(0)
	s_barrier
	v_cmp_lt_i32_e32 vcc, s2, v2
	v_readfirstlane_b32 s4, v2
	s_mov_b64 s[2:3], -1
	s_cbranch_vccnz .LBB0_670
	s_add_i32 s5, s4, s63
	s_cmpk_lt_i32 s5, 0x600
	s_mul_hi_i32 s34, s5, 0x2aaaaaab
	s_cselect_b64 s[2:3], -1, 0
	s_lshr_b32 s38, s34, 31
	s_ashr_i32 s34, s34, 3
	s_add_i32 s38, s34, s38
	s_mul_i32 s34, s38, 48
	s_sub_i32 s34, s5, s34
	s_and_b32 s5, s38, 1
	s_ashr_i32 s38, s38, 1
	s_sub_i32 s39, 15, s38
	s_add_i32 s38, s38, 16
	s_cmp_eq_u32 s5, 0
	s_mul_hi_i32 s5, s4, 0x2aaaaaab
	s_cselect_b32 s48, s38, s39
	s_lshr_b32 s38, s5, 31
	s_lshr_b32 s5, s5, 3
	s_add_i32 s5, s5, s38
	s_mul_i32 s5, s5, 48
	s_sub_i32 s38, s4, s5
	v_cndmask_b32_e64 v2, 0, 1, s[2:3]
	s_mov_b64 s[4:5], -1
	s_cmp_gt_i32 s38, 31
	v_cmp_ne_u32_e64 s[2:3], 1, v2
	s_cbranch_scc0 .LBB0_697
	v_mov_b32_e32 v66, v0
	s_sub_i32 s49, s34, 32
	v_and_b32_e32 v70, 0xff, v66
	s_and_b64 vcc, exec, s[2:3]
	v_readfirstlane_b32 s50, v70
	v_and_b32_e32 v71, 31, v66
	s_cbranch_vccnz .LBB0_694
	s_lshl_b32 s4, s49, 5
	s_add_i32 s38, s48, s4
	s_ashr_i32 s39, s38, 31
	s_lshl_b64 s[4:5], s[38:39], 5
	s_add_u32 s42, s91, s4
	v_readlane_b32 s24, v250, 0
	s_addc_u32 s43, s90, s5
	s_lshl_b64 s[4:5], s[38:39], 16
	v_readlane_b32 s30, v250, 6
	v_readlane_b32 s31, v250, 7
	s_add_u32 s4, s30, s4
	v_mov_b32_e32 v2, s50
	s_movk_i32 s40, 0xffc0
	s_addc_u32 s5, s31, s5
	v_bfi_b32 v2, s40, v2, v66
	s_add_u32 s4, s4, 0xdc78000
	v_add_u32_e32 v6, 0x100, v2
	v_add_u32_e32 v8, 0x200, v2
	v_add_u32_e32 v10, 0x300, v2
	s_addc_u32 s5, s5, 0
	v_ashrrev_i32_e32 v3, 31, v2
	v_ashrrev_i32_e32 v7, 31, v6
	v_ashrrev_i32_e32 v9, 31, v8
	v_ashrrev_i32_e32 v11, 31, v10
	v_lshl_add_u64 v[4:5], v[2:3], 3, s[4:5]
	v_lshl_add_u64 v[6:7], v[6:7], 3, s[4:5]
	v_lshl_add_u64 v[8:9], v[8:9], 3, s[4:5]
	v_lshl_add_u64 v[10:11], v[10:11], 3, s[4:5]
	global_load_dwordx2 v[62:63], v[4:5], off
	global_load_dwordx2 v[42:43], v[6:7], off
	global_load_dwordx2 v[38:39], v[8:9], off
	global_load_dwordx2 v[34:35], v[10:11], off
	v_add_u32_e32 v4, 0x400, v2
	v_add_u32_e32 v6, 0x500, v2
	v_add_u32_e32 v8, 0x600, v2
	v_add_u32_e32 v10, 0x700, v2
	v_ashrrev_i32_e32 v5, 31, v4
	v_ashrrev_i32_e32 v7, 31, v6
	v_ashrrev_i32_e32 v9, 31, v8
	v_ashrrev_i32_e32 v11, 31, v10
	v_lshl_add_u64 v[4:5], v[4:5], 3, s[4:5]
	v_lshl_add_u64 v[6:7], v[6:7], 3, s[4:5]
	v_lshl_add_u64 v[8:9], v[8:9], 3, s[4:5]
	v_lshl_add_u64 v[10:11], v[10:11], 3, s[4:5]
	global_load_dwordx2 v[32:33], v[4:5], off
	global_load_dwordx2 v[26:27], v[6:7], off
	global_load_dwordx2 v[22:23], v[8:9], off
	global_load_dwordx2 v[18:19], v[10:11], off
	v_add_u32_e32 v4, 0x800, v2
	v_add_u32_e32 v6, 0x900, v2
	v_add_u32_e32 v8, 0xa00, v2
	v_add_u32_e32 v10, 0xb00, v2
	v_ashrrev_i32_e32 v5, 31, v4
	v_ashrrev_i32_e32 v7, 31, v6
	v_ashrrev_i32_e32 v9, 31, v8
	v_ashrrev_i32_e32 v11, 31, v10
	v_lshl_add_u64 v[4:5], v[4:5], 3, s[4:5]
	v_lshl_add_u64 v[6:7], v[6:7], 3, s[4:5]
	v_lshl_add_u64 v[8:9], v[8:9], 3, s[4:5]
	v_lshl_add_u64 v[10:11], v[10:11], 3, s[4:5]
	global_load_dwordx2 v[16:17], v[4:5], off
	global_load_dwordx2 v[14:15], v[6:7], off
	global_load_dwordx2 v[12:13], v[8:9], off
	s_nop 0
	global_load_dwordx2 v[10:11], v[10:11], off
	v_add_u32_e32 v4, 0xc00, v2
	v_add_u32_e32 v6, 0xd00, v2
	v_add_u32_e32 v8, 0xe00, v2
	v_add_u32_e32 v2, 0xf00, v2
	v_ashrrev_i32_e32 v5, 31, v4
	v_ashrrev_i32_e32 v7, 31, v6
	v_ashrrev_i32_e32 v3, 31, v2
	v_lshl_add_u64 v[4:5], v[4:5], 3, s[4:5]
	v_lshl_add_u64 v[6:7], v[6:7], 3, s[4:5]
	v_ashrrev_i32_e32 v9, 31, v8
	v_lshl_add_u64 v[2:3], v[2:3], 3, s[4:5]
	v_lshl_add_u64 v[20:21], v[8:9], 3, s[4:5]
	global_load_dwordx2 v[8:9], v[4:5], off
	s_nop 0
	global_load_dwordx2 v[6:7], v[6:7], off
	s_nop 0
	global_load_dwordx2 v[4:5], v[20:21], off
	s_nop 0
	global_load_dwordx2 v[2:3], v[2:3], off
	v_and_b32_e32 v20, 63, v66
	v_lshlrev_b32_e32 v130, 2, v20
	s_and_b32 s40, s50, 0xffffffc0
	v_cmp_gt_u32_e64 s[4:5], 8, v20
	v_lshl_add_u64 v[24:25], s[42:43], 0, v[130:131]
	s_mov_b32 s41, 0x400000
	v_readlane_b32 s25, v250, 1
	v_readlane_b32 s26, v250, 2
	v_readlane_b32 s27, v250, 3
	v_readlane_b32 s28, v250, 4
	v_readlane_b32 s29, v250, 5
	s_branch .LBB0_680
